# token0 exact projection: 16 weight-row loads per unrolled step issued together
# baseline (speedup 1.0000x reference)
; #define LAS __attribute__((address_space(3)))
; DI void token0_task(ldsp lds, const float* xcur, size_t xstride, const float* nw, const float* win, float* q0k0, int task, int tid, int wid, int lane) {
;     ...
;     if (tid < 504) {
;         const int g4 = tid % 24, sl = tid / 24, k_lo = sl * 49, k_hi = (k_lo + 49 < 1024) ? k_lo + 49 : 1024;
;         f32x4 acc = (f32x4){0.f, 0.f, 0.f, 0.f};
;         const float* wp = win + (size_t)k_lo * GLA_N + grp * 96 + g4 * 4;
; #pragma unroll 16
;         for (int k = k_lo; k < k_hi; ++k, wp += GLA_N) { const f32x4 w = *(const f32x4*)wp; acc += w * HX[k]; }
;         *(LAS f32x4*)(PART + sl * 96 + g4 * 4) = acc;
;     }
.LBB0_821:
	s_mov_b64 s[98:99], 0x2c40
	s_mov_b64 s[34:35], 0x2c400
	ds_read2_b32 v[108:109], v14 offset0:0 offset1:1
	ds_read2_b32 v[110:111], v14 offset0:2 offset1:3
	ds_read2_b32 v[112:113], v14 offset0:4 offset1:5
	ds_read2_b32 v[114:115], v14 offset0:6 offset1:7
	ds_read2_b32 v[116:117], v14 offset0:8 offset1:9
	ds_read2_b32 v[118:119], v14 offset0:10 offset1:11
	ds_read2_b32 v[120:121], v14 offset0:12 offset1:13
	ds_read2_b32 v[122:123], v14 offset0:14 offset1:15
	global_load_dwordx4 v[44:47], v[10:11], off
	v_lshl_add_u64 v[124:125], v[10:11], 0, s[98:99]
	global_load_dwordx4 v[48:51], v[124:125], off
	v_lshl_add_u64 v[126:127], v[124:125], 0, s[98:99]
	global_load_dwordx4 v[52:55], v[126:127], off
	v_lshl_add_u64 v[124:125], v[126:127], 0, s[98:99]
	global_load_dwordx4 v[56:59], v[124:125], off
	v_lshl_add_u64 v[126:127], v[124:125], 0, s[98:99]
	global_load_dwordx4 v[60:63], v[126:127], off
	v_lshl_add_u64 v[124:125], v[126:127], 0, s[98:99]
	global_load_dwordx4 v[64:67], v[124:125], off
	v_lshl_add_u64 v[126:127], v[124:125], 0, s[98:99]
	global_load_dwordx4 v[68:71], v[126:127], off
	v_lshl_add_u64 v[124:125], v[126:127], 0, s[98:99]
	global_load_dwordx4 v[72:75], v[124:125], off
	v_lshl_add_u64 v[126:127], v[124:125], 0, s[98:99]
	global_load_dwordx4 v[76:79], v[126:127], off
	v_lshl_add_u64 v[124:125], v[126:127], 0, s[98:99]
	global_load_dwordx4 v[80:83], v[124:125], off
	v_lshl_add_u64 v[126:127], v[124:125], 0, s[98:99]
	global_load_dwordx4 v[84:87], v[126:127], off
	v_lshl_add_u64 v[124:125], v[126:127], 0, s[98:99]
	global_load_dwordx4 v[88:91], v[124:125], off
	v_lshl_add_u64 v[126:127], v[124:125], 0, s[98:99]
	global_load_dwordx4 v[92:95], v[126:127], off
	v_lshl_add_u64 v[124:125], v[126:127], 0, s[98:99]
	global_load_dwordx4 v[96:99], v[124:125], off
	v_lshl_add_u64 v[126:127], v[124:125], 0, s[98:99]
	global_load_dwordx4 v[100:103], v[126:127], off
	v_lshl_add_u64 v[124:125], v[126:127], 0, s[98:99]
	global_load_dwordx4 v[104:107], v[124:125], off
	v_add_u32_e32 v13, 16, v13
	v_add_u32_e32 v14, 64, v14
	v_lshl_add_u64 v[10:11], v[10:11], 0, s[34:35]
	s_waitcnt vmcnt(15) lgkmcnt(7)
	v_pk_fma_f32 v[0:1], v[44:45], v[108:109], v[0:1] op_sel_hi:[1,0,1]
	v_pk_fma_f32 v[2:3], v[46:47], v[108:109], v[2:3] op_sel_hi:[1,0,1]
	s_waitcnt vmcnt(14)
	v_pk_fma_f32 v[0:1], v[48:49], v[108:109], v[0:1] op_sel:[0,1,0]
	v_pk_fma_f32 v[2:3], v[50:51], v[108:109], v[2:3] op_sel:[0,1,0]
	s_waitcnt vmcnt(13) lgkmcnt(6)
	v_pk_fma_f32 v[0:1], v[52:53], v[110:111], v[0:1] op_sel_hi:[1,0,1]
	v_pk_fma_f32 v[2:3], v[54:55], v[110:111], v[2:3] op_sel_hi:[1,0,1]
	s_waitcnt vmcnt(12)
	v_pk_fma_f32 v[0:1], v[56:57], v[110:111], v[0:1] op_sel:[0,1,0]
	v_pk_fma_f32 v[2:3], v[58:59], v[110:111], v[2:3] op_sel:[0,1,0]
	s_waitcnt vmcnt(11) lgkmcnt(5)
	v_pk_fma_f32 v[0:1], v[60:61], v[112:113], v[0:1] op_sel_hi:[1,0,1]
	v_pk_fma_f32 v[2:3], v[62:63], v[112:113], v[2:3] op_sel_hi:[1,0,1]
	s_waitcnt vmcnt(10)
	v_pk_fma_f32 v[0:1], v[64:65], v[112:113], v[0:1] op_sel:[0,1,0]
	v_pk_fma_f32 v[2:3], v[66:67], v[112:113], v[2:3] op_sel:[0,1,0]
	s_waitcnt vmcnt(9) lgkmcnt(4)
	v_pk_fma_f32 v[0:1], v[68:69], v[114:115], v[0:1] op_sel_hi:[1,0,1]
	v_pk_fma_f32 v[2:3], v[70:71], v[114:115], v[2:3] op_sel_hi:[1,0,1]
	s_waitcnt vmcnt(8)
	v_pk_fma_f32 v[0:1], v[72:73], v[114:115], v[0:1] op_sel:[0,1,0]
	v_pk_fma_f32 v[2:3], v[74:75], v[114:115], v[2:3] op_sel:[0,1,0]
	s_waitcnt vmcnt(7) lgkmcnt(3)
	v_pk_fma_f32 v[0:1], v[76:77], v[116:117], v[0:1] op_sel_hi:[1,0,1]
	v_pk_fma_f32 v[2:3], v[78:79], v[116:117], v[2:3] op_sel_hi:[1,0,1]
	s_waitcnt vmcnt(6)
	v_pk_fma_f32 v[0:1], v[80:81], v[116:117], v[0:1] op_sel:[0,1,0]
	v_pk_fma_f32 v[2:3], v[82:83], v[116:117], v[2:3] op_sel:[0,1,0]
	s_waitcnt vmcnt(5) lgkmcnt(2)
	v_pk_fma_f32 v[0:1], v[84:85], v[118:119], v[0:1] op_sel_hi:[1,0,1]
	v_pk_fma_f32 v[2:3], v[86:87], v[118:119], v[2:3] op_sel_hi:[1,0,1]
	s_waitcnt vmcnt(4)
	v_pk_fma_f32 v[0:1], v[88:89], v[118:119], v[0:1] op_sel:[0,1,0]
	v_pk_fma_f32 v[2:3], v[90:91], v[118:119], v[2:3] op_sel:[0,1,0]
	s_waitcnt vmcnt(3) lgkmcnt(1)
	v_pk_fma_f32 v[0:1], v[92:93], v[120:121], v[0:1] op_sel_hi:[1,0,1]
	v_pk_fma_f32 v[2:3], v[94:95], v[120:121], v[2:3] op_sel_hi:[1,0,1]
	s_waitcnt vmcnt(2)
	v_pk_fma_f32 v[0:1], v[96:97], v[120:121], v[0:1] op_sel:[0,1,0]
	v_pk_fma_f32 v[2:3], v[98:99], v[120:121], v[2:3] op_sel:[0,1,0]
	s_waitcnt vmcnt(1) lgkmcnt(0)
	v_pk_fma_f32 v[0:1], v[100:101], v[122:123], v[0:1] op_sel_hi:[1,0,1]
	v_pk_fma_f32 v[2:3], v[102:103], v[122:123], v[2:3] op_sel_hi:[1,0,1]
	s_waitcnt vmcnt(0)
	v_pk_fma_f32 v[0:1], v[104:105], v[122:123], v[0:1] op_sel:[0,1,0]
	v_pk_fma_f32 v[2:3], v[106:107], v[122:123], v[2:3] op_sel:[0,1,0]
	v_cmp_ge_i32_e32 vcc, v13, v24
	s_or_b64 s[36:37], vcc, s[36:37]
	s_andn2_b64 exec, exec, s[36:37]
	s_cbranch_execnz .LBB0_821
	s_or_b64 exec, exec, s[36:37]
